# v33 + one static s_setprio 1 at kernel entry for waves 4-7 (younger half), no per-segment toggling
# baseline (speedup 1.0000x reference)
_Z10fwd_kernel6Params:
	s_load_dwordx2 s[18:19], s[0:1], 0x98
	s_mov_b64 s[16:17], s[0:1]
	s_add_u32 s4, s16, 0x98
	v_and_b32_e32 v161, 0x3ff, v0
	s_mov_b32 s12, s2
	s_addc_u32 s5, s17, 0
	v_readfirstlane_b32 s100, v161
	s_cmp_lt_u32 s100, 0x100
	s_cbranch_scc1 .Lprio_skip
	s_setprio 1
.Lprio_skip:
	v_cmp_gt_u32_e32 vcc, 32, v161
	s_and_saveexec_b64 s[0:1], vcc
	v_lshl_add_u32 v1, v161, 2, 0
	v_add_u32_e32 v1, 0x20140, v1
	v_mov_b32_e32 v2, 0
	ds_write_b32 v1, v2
	s_or_b64 exec, exec, s[0:1]
	s_load_dword s0, s[16:17], 0x90
	s_load_dwordx2 s[20:21], s[16:17], 0x88
	s_waitcnt lgkmcnt(0)
	s_cmp_gt_i32 s0, -1
	s_cbranch_scc1 .LBB0_14
	v_lshrrev_b32_e32 v1, 20, v0
	v_lshrrev_b32_e32 v0, 10, v0
	v_or_b32_e32 v0, v0, v1
	s_movk_i32 s0, 0x3ff
	v_and_or_b32 v0, v0, s0, v161
	v_cmp_eq_u32_e32 vcc, 0, v0
	s_barrier
	s_and_saveexec_b64 s[0:1], vcc
	s_cbranch_execz .LBB0_13
	buffer_wbl2 sc1
	s_load_dwordx2 s[4:5], s[4:5], 0x58
	s_mov_b64 s[6:7], exec
	v_mbcnt_lo_u32_b32 v0, s6, 0
	v_mbcnt_hi_u32_b32 v0, s7, v0
	v_cmp_eq_u32_e32 vcc, 0, v0
	s_waitcnt lgkmcnt(0)
	s_load_dword s2, s[4:5], 0x28
	s_and_saveexec_b64 s[8:9], vcc
	s_cbranch_execz .LBB0_6
	s_bcnt1_i32_b64 s3, s[6:7]
	v_mov_b32_e32 v1, 0
	v_mov_b32_e32 v2, s3
	global_atomic_add v1, v1, v2, s[4:5] offset:32 sc0

	.amdhsa_kernel _Z10fwd_kernel6Params
		.amdhsa_group_segment_fixed_size 0
		.amdhsa_private_segment_fixed_size 0
		.amdhsa_kernarg_size 408
		.amdhsa_user_sgpr_count 2
		.amdhsa_user_sgpr_dispatch_ptr 0
		.amdhsa_user_sgpr_queue_ptr 0
		.amdhsa_user_sgpr_kernarg_segment_ptr 1
		.amdhsa_user_sgpr_dispatch_id 0
		.amdhsa_user_sgpr_kernarg_preload_length 0
		.amdhsa_user_sgpr_kernarg_preload_offset 0
		.amdhsa_user_sgpr_private_segment_size 0
		.amdhsa_uses_dynamic_stack 0
		.amdhsa_enable_private_segment 0
		.amdhsa_system_sgpr_workgroup_id_x 1
		.amdhsa_system_sgpr_workgroup_id_y 0
		.amdhsa_system_sgpr_workgroup_id_z 0
		.amdhsa_system_sgpr_workgroup_info 0
		.amdhsa_system_vgpr_workitem_id 2
		.amdhsa_next_free_vgpr 256
		.amdhsa_next_free_sgpr 102
		.amdhsa_accum_offset 256
		.amdhsa_reserve_vcc 1
		.amdhsa_float_round_mode_32 0
		.amdhsa_float_round_mode_16_64 0
		.amdhsa_float_denorm_mode_32 3
		.amdhsa_float_denorm_mode_16_64 3
		.amdhsa_dx10_clamp 1
		.amdhsa_ieee_mode 1
		.amdhsa_fp16_overflow 0
		.amdhsa_tg_split 0
		.amdhsa_exception_fp_ieee_invalid_op 0
		.amdhsa_exception_fp_denorm_src 0
		.amdhsa_exception_fp_ieee_div_zero 0
		.amdhsa_exception_fp_ieee_overflow 0
		.amdhsa_exception_fp_ieee_underflow 0
		.amdhsa_exception_fp_ieee_inexact 0
		.amdhsa_exception_int_div_zero 0
	.end_amdhsa_kernel

amdhsa.kernels:
  - .agpr_count:     0
    .args:
      - .offset:         0
        .size:           152
        .value_kind:     by_value
      - .offset:         152
        .size:           4
        .value_kind:     hidden_block_count_x
      - .offset:         156
        .size:           4
        .value_kind:     hidden_block_count_y
      - .offset:         160
        .size:           4
        .value_kind:     hidden_block_count_z
      - .offset:         164
        .size:           2
        .value_kind:     hidden_group_size_x
      - .offset:         166
        .size:           2
        .value_kind:     hidden_group_size_y
      - .offset:         168
        .size:           2
        .value_kind:     hidden_group_size_z
      - .offset:         170
        .size:           2
        .value_kind:     hidden_remainder_x
      - .offset:         172
        .size:           2
        .value_kind:     hidden_remainder_y
      - .offset:         174
        .size:           2
        .value_kind:     hidden_remainder_z
      - .offset:         192
        .size:           8
        .value_kind:     hidden_global_offset_x
      - .offset:         200
        .size:           8
        .value_kind:     hidden_global_offset_y
      - .offset:         208
        .size:           8
        .value_kind:     hidden_global_offset_z
      - .offset:         216
        .size:           2
        .value_kind:     hidden_grid_dims
      - .offset:         240
        .size:           8
        .value_kind:     hidden_multigrid_sync_arg
      - .offset:         272
        .size:           4
        .value_kind:     hidden_dynamic_lds_size
    .group_segment_fixed_size: 0
    .kernarg_segment_align: 8
    .kernarg_segment_size: 408
    .language:       OpenCL C
    .language_version:
      - 2
      - 0
    .max_flat_workgroup_size: 512
    .name:           _Z10fwd_kernel6Params
    .private_segment_fixed_size: 0
    .sgpr_count:     108
    .sgpr_spill_count: 239
    .symbol:         _Z10fwd_kernel6Params.kd
    .uniform_work_group_size: 1
    .uses_dynamic_stack: false
    .vgpr_count:     256
    .vgpr_spill_count: 0
    .wavefront_size: 64
